# c22 + removed the now-unused panel-counter increments (mbcnt + atomic add) in the three fused-LN epilogues
# baseline (speedup 1.0000x reference)
;     __device__ __forceinline__ void fused(AccT& acc, const Unit& u, int wr, int wc, int fr_in, int fq_in, LAS unsigned char* lds, int wid, int lane_in) const {
;     ...
;         if (lane == 0) __hip_atomic_fetch_add(cnt + 64 * u.pm, 1u, __ATOMIC_RELAXED, __HIP_MEMORY_SCOPE_AGENT);
.LBB0_1069:
	s_or_b64 exec, exec, s[18:19]
	v_cmp_eq_u32_e64 s[40:41], 0, v218
.LBB0_1087:
	s_and_saveexec_b64 s[16:17], s[38:39]
	s_cbranch_execz .LBB0_1089
	v_readlane_b32 s0, v253, 9
	v_lshlrev_b64 v[164:165], 6, v[164:165]
	v_readlane_b32 s1, v253, 10
	v_lshl_add_u32 v1, v1, 3, 0
	s_nop 0
	v_lshl_add_u64 v[164:165], s[0:1], 0, v[164:165]
	s_mov_b32 s20, 0

;     __device__ __forceinline__ void fused(AccT& acc, const Unit& u, int wr, int wc, int fr_in, int fq_in, LAS unsigned char* lds, int wid, int lane_in) const {
;     ...
;         if (lane == 0) __hip_atomic_fetch_add(cnt + 64 * u.pm, 1u, __ATOMIC_RELAXED, __HIP_MEMORY_SCOPE_AGENT);
.LBB0_1251:
	s_or_b64 exec, exec, s[18:19]
	v_cmp_eq_u32_e64 s[40:41], 0, v218
.LBB0_1269:
	s_and_saveexec_b64 s[16:17], s[38:39]
	s_cbranch_execz .LBB0_1271
	v_readlane_b32 s0, v253, 9
	v_lshlrev_b64 v[164:165], 6, v[164:165]
	v_readlane_b32 s1, v253, 10
	v_lshl_add_u32 v1, v1, 3, 0
	s_nop 0
	v_lshl_add_u64 v[164:165], s[0:1], 0, v[164:165]
	s_mov_b32 s20, 0

;     __device__ __forceinline__ void fused(AccT& acc, const Unit& u, int wr, int wc, int fr_in, int fq_in, LAS unsigned char* lds, int wid, int lane_in) const {
;     ...
;         if (lane == 0) __hip_atomic_fetch_add(cnt + 64 * u.pm, 1u, __ATOMIC_RELAXED, __HIP_MEMORY_SCOPE_AGENT);
.LBB0_1312:
	s_or_b64 exec, exec, s[18:19]
	v_cmp_eq_u32_e64 s[38:39], 0, v207
.LBB0_1330:
	s_and_saveexec_b64 s[16:17], s[36:37]
	s_cbranch_execz .LBB0_1332
	v_readlane_b32 s0, v253, 9
	v_lshlrev_b64 v[166:167], 6, v[166:167]
	v_readlane_b32 s1, v253, 10
	v_lshl_add_u32 v1, v1, 3, 0
	s_nop 0
	v_lshl_add_u64 v[166:167], s[0:1], 0, v[166:167]
	s_mov_b32 s2, 0
